# attention compute segments at s_setprio 1 + downstream GEMM phases restored to baseline byte alignment
# speedup vs baseline: 1.0060x; 1.0060x over previous
; #define SEAM(k) do { if (IN(k) && IN((k) + 1)) xcd_barrier(xbar); } while (0)
; __device__ __forceinline__ void xcd_barrier(const XcdBarrier& b) {
;     asm volatile("s_waitcnt vmcnt(0)" ::: "memory");
;     __syncthreads();
;     if (threadIdx.x == 0) {
;         unsigned* bar = b.bar;
;         __builtin_amdgcn_s_waitcnt(0);
;         unsigned nloc = b.st[0], nx = b.st[1];
;         if (nloc == 0u) { xcd_barrier_complete(bar, b.x, nloc, nx); b.st[0] = nloc; b.st[1] = nx; }
; __global__ void __launch_bounds__(512, 2) fwd_megakernel(Args args) {
;     ...
;     SEAM(3);
.LBB0_606:
	s_nop 0
	s_nop 0
	s_nop 0
	s_nop 0
	s_nop 0
	s_nop 0
	s_nop 0
	s_nop 0
	s_nop 0
	s_nop 0
	s_nop 0
	s_nop 0
	s_nop 0
	s_nop 0
	s_nop 0
	s_cmp_gt_i32 s31, 4
	s_cselect_b64 s[2:3], -1, 0
	s_and_b64 s[0:1], s[0:1], s[2:3]
	s_andn2_b64 vcc, exec, s[0:1]
	s_cbranch_vccnz .LBB0_660
	s_waitcnt vmcnt(0)
	s_waitcnt vmcnt(0) lgkmcnt(0)
	s_barrier
	s_and_saveexec_b64 s[0:1], s[82:83]
	s_cbranch_execz .LBB0_659
	s_add_i32 s4, 0, 0x22000
	v_mov_b32_e32 v0, s4
	s_waitcnt vmcnt(0) expcnt(0) lgkmcnt(0)
	ds_read_b32 v2, v0
	s_add_i32 s4, 0, 0x22004
	v_mov_b32_e32 v0, s4
	ds_read_b32 v0, v0
	s_waitcnt lgkmcnt(1)
	v_cmp_ne_u32_e32 vcc, 0, v2
	s_cbranch_vccnz .LBB0_623
	v_readlane_b32 s4, v254, 0
	s_mul_i32 s18, s93, s4
	s_add_u32 s4, s28, 0x1000
	s_addc_u32 s5, s29, 0
	s_add_u32 s6, s28, 0x1100
	s_addc_u32 s7, s29, 0
	s_add_u32 s8, s28, 0x1200
	s_addc_u32 s9, s29, 0
	s_add_u32 s10, s28, 0x1300
	s_mul_i32 s18, s18, s92
	s_addc_u32 s11, s29, 0
	s_mov_b32 s19, 1
	v_mov_b32_e32 v16, 0
	s_branch .LBB0_611
